# E20: grid barrier waiters poll the cross-XCD arrival counter directly (no separate release word, one round trip less per barrier), on E10
# speedup vs baseline: 1.0055x; 1.0055x over previous
.LBB0_74:
	s_or_b64 exec, exec, s[6:7]
	v_cvt_f32_u32_e32 v4, v2
	s_waitcnt vmcnt(0)
	v_readfirstlane_b32 s6, v3
	v_sub_u32_e32 v3, 0, v2
	v_rcp_iflag_f32_e32 v4, v4
	v_add_u32_e32 v5, s6, v1
	v_mul_f32_e32 v4, 0x4f7ffffe, v4
	v_cvt_u32_f32_e32 v4, v4
	v_mul_lo_u32 v1, v3, v4
	v_mul_hi_u32 v1, v4, v1
	v_add_u32_e32 v1, v4, v1
	v_mul_hi_u32 v1, v5, v1
	v_mul_lo_u32 v3, v1, v2
	v_sub_u32_e32 v3, v5, v3
	v_add_u32_e32 v4, 1, v1
	v_cmp_ge_u32_e32 vcc, v3, v2
	s_nop 1
	v_cndmask_b32_e32 v1, v1, v4, vcc
	v_sub_u32_e32 v4, v3, v2
	v_cndmask_b32_e32 v3, v3, v4, vcc
	v_add_u32_e32 v4, 1, v1
	v_cmp_ge_u32_e32 vcc, v3, v2
	v_add_u32_e32 v3, 1, v5
	s_nop 0
	v_cndmask_b32_e32 v1, v1, v4, vcc
	v_mul_lo_u32 v4, v2, v1
	v_add_u32_e32 v2, v4, v2
	v_cmp_ne_u32_e32 vcc, v3, v2
	s_and_saveexec_b64 s[6:7], vcc
	s_xor_b64 s[6:7], exec, s[6:7]
	s_cbranch_execz .LBB0_88
	s_waitcnt lgkmcnt(0)
	v_add_u32_e32 v1, 1, v1
	v_mul_lo_u32 v1, v1, v0
	v_mov_b32_e32 v0, 0x7000
	buffer_inv sc1
	global_load_dword v0, v0, s[0:1] offset:1024 sc1
	s_add_u32 s12, s0, 0x7400
	s_addc_u32 s13, s1, 0
	s_waitcnt vmcnt(0)
	v_cmp_lt_u32_e32 vcc, v0, v1
	s_and_saveexec_b64 s[8:9], vcc
	s_cbranch_execz .LBB0_87
	s_add_u32 s10, s0, 0x4200
	s_addc_u32 s11, s1, 0
	s_mov_b32 s24, 1
	s_mov_b64 s[14:15], 0
	v_mov_b32_e32 v0, 0
	s_branch .LBB0_78

.LBB0_80:
	global_load_dword v2, v0, s[12:13] sc1
	s_add_i32 s24, s24, 1
	s_mov_b64 s[20:21], -1
	s_waitcnt vmcnt(0)
	v_cmp_ge_u32_e32 vcc, v2, v1
	s_orn2_b64 s[18:19], vcc, exec
	s_branch .LBB0_77

.LBB0_91:
	s_or_b64 exec, exec, s[8:9]
	v_cvt_f32_u32_e32 v3, v0
	s_waitcnt vmcnt(0)
	v_readfirstlane_b32 s6, v2
	s_add_u32 s8, s0, 0x7400
	s_addc_u32 s9, s1, 0
	v_rcp_iflag_f32_e32 v3, v3
	v_add_u32_e32 v1, s6, v1
	v_add_u32_e32 v4, 1, v1
	s_mov_b64 s[10:11], 0
	v_mul_f32_e32 v2, 0x4f7ffffe, v3
	v_cvt_u32_f32_e32 v2, v2
	v_sub_u32_e32 v3, 0, v0
	v_mul_lo_u32 v3, v3, v2
	v_mul_hi_u32 v3, v2, v3
	v_add_u32_e32 v2, v2, v3
	v_mul_hi_u32 v2, v1, v2
	v_mul_lo_u32 v3, v2, v0
	v_sub_u32_e32 v1, v1, v3
	v_add_u32_e32 v5, 1, v2
	v_cmp_ge_u32_e32 vcc, v1, v0
	v_sub_u32_e32 v3, v1, v0
	s_nop 0
	v_cndmask_b32_e32 v2, v2, v5, vcc
	v_cndmask_b32_e32 v1, v1, v3, vcc
	v_add_u32_e32 v3, 1, v2
	v_cmp_ge_u32_e32 vcc, v1, v0
	s_nop 1
	v_cndmask_b32_e32 v2, v2, v3, vcc
	v_mul_lo_u32 v1, v0, v2
	v_add_u32_e32 v0, v1, v0
	v_mov_b32_e32 v6, v0
	v_cmp_ne_u32_e32 vcc, v4, v0
	v_mov_b64_e32 v[0:1], s[8:9]
	s_and_saveexec_b64 s[6:7], vcc
	s_cbranch_execz .LBB0_103
	v_mov_b32_e32 v0, 0
	global_load_dword v1, v0, s[8:9] sc1
	s_mov_b64 s[14:15], 0
	s_waitcnt vmcnt(0)
	v_cmp_lt_u32_e32 vcc, v1, v6
	s_and_saveexec_b64 s[12:13], vcc
	s_cbranch_execz .LBB0_102
	s_add_u32 s10, s0, 0x4200
	s_addc_u32 s11, s1, 0
	s_mov_b32 s24, 1
	s_branch .LBB0_95

.LBB0_97:
	global_load_dword v1, v0, s[8:9] sc1
	s_add_i32 s24, s24, 1
	s_mov_b64 s[18:19], -1
	s_waitcnt vmcnt(0)
	v_cmp_ge_u32_e32 vcc, v1, v6
	s_orn2_b64 s[22:23], vcc, exec
	s_branch .LBB0_94

.LBB0_1292:
	s_or_b64 exec, exec, s[6:7]
	v_cvt_f32_u32_e32 v5, v2
	s_waitcnt vmcnt(0)
	v_readfirstlane_b32 s6, v4
	v_sub_u32_e32 v4, 0, v2
	v_rcp_iflag_f32_e32 v5, v5
	v_add_u32_e32 v6, s6, v1
	v_mul_f32_e32 v5, 0x4f7ffffe, v5
	v_cvt_u32_f32_e32 v5, v5
	v_mul_lo_u32 v1, v4, v5
	v_mul_hi_u32 v1, v5, v1
	v_add_u32_e32 v1, v5, v1
	v_mul_hi_u32 v1, v6, v1
	v_mul_lo_u32 v4, v1, v2
	v_sub_u32_e32 v4, v6, v4
	v_add_u32_e32 v5, 1, v1
	v_cmp_ge_u32_e32 vcc, v4, v2
	s_nop 1
	v_cndmask_b32_e32 v1, v1, v5, vcc
	v_sub_u32_e32 v5, v4, v2
	v_cndmask_b32_e32 v4, v4, v5, vcc
	v_add_u32_e32 v5, 1, v1
	v_cmp_ge_u32_e32 vcc, v4, v2
	v_add_u32_e32 v4, 1, v6
	s_nop 0
	v_cndmask_b32_e32 v1, v1, v5, vcc
	v_mul_lo_u32 v5, v2, v1
	v_add_u32_e32 v2, v5, v2
	v_cmp_ne_u32_e32 vcc, v4, v2
	s_and_saveexec_b64 s[6:7], vcc
	s_xor_b64 s[6:7], exec, s[6:7]
	s_cbranch_execz .LBB0_1306
	v_readlane_b32 s8, v253, 26
	v_readlane_b32 s9, v253, 27
	s_waitcnt lgkmcnt(0)
	v_add_u32_e32 v1, 1, v1
	v_mul_lo_u32 v1, v1, v0
	buffer_inv sc1
	s_nop 2
	global_load_dword v0, v3, s[8:9] sc1
	s_waitcnt vmcnt(0)
	v_cmp_lt_u32_e32 vcc, v0, v1
	s_and_saveexec_b64 s[8:9], vcc
	s_cbranch_execz .LBB0_1305
	s_mov_b32 s21, s15
	s_mov_b32 s20, 1
	s_mov_b64 s[10:11], 0
	s_branch .LBB0_1296

.LBB0_1298:
	v_readlane_b32 s14, v253, 26
	v_readlane_b32 s15, v253, 27
	s_add_i32 s20, s20, 1
	s_mov_b64 s[16:17], -1
	s_nop 2
	global_load_dword v0, v3, s[14:15] sc1
	s_waitcnt vmcnt(0)
	v_cmp_ge_u32_e32 vcc, v0, v1
	s_orn2_b64 s[14:15], vcc, exec
	s_branch .LBB0_1295

.LBB0_1309:
	s_or_b64 exec, exec, s[8:9]
	s_waitcnt vmcnt(0)
	v_readfirstlane_b32 s6, v2
	v_cvt_f32_u32_e32 v2, v0
	v_sub_u32_e32 v4, 0, v0
	v_add_u32_e32 v1, s6, v1
	v_readlane_b32 s6, v253, 24
	v_rcp_iflag_f32_e32 v2, v2
	v_readlane_b32 s7, v253, 25
	s_mov_b64 s[8:9], 0
	v_mul_f32_e32 v2, 0x4f7ffffe, v2
	v_cvt_u32_f32_e32 v2, v2
	v_mul_lo_u32 v4, v4, v2
	v_mul_hi_u32 v4, v2, v4
	v_add_u32_e32 v2, v2, v4
	v_mul_hi_u32 v2, v1, v2
	v_mul_lo_u32 v4, v2, v0
	v_sub_u32_e32 v4, v1, v4
	v_cmp_ge_u32_e32 vcc, v4, v0
	v_add_u32_e32 v5, 1, v2
	v_add_u32_e32 v1, 1, v1
	v_cndmask_b32_e32 v2, v2, v5, vcc
	v_sub_u32_e32 v5, v4, v0
	v_cndmask_b32_e32 v4, v4, v5, vcc
	v_cmp_ge_u32_e32 vcc, v4, v0
	v_add_u32_e32 v4, 1, v2
	s_nop 0
	v_cndmask_b32_e32 v2, v2, v4, vcc
	v_mul_lo_u32 v4, v0, v2
	v_add_u32_e32 v0, v4, v0
	v_mov_b32_e32 v6, v0
	v_cmp_ne_u32_e32 vcc, v1, v0
	v_mov_b64_e32 v[0:1], s[6:7]
	s_and_saveexec_b64 s[6:7], vcc
	s_cbranch_execz .LBB0_1321
	v_readlane_b32 s8, v253, 26
	v_readlane_b32 s9, v253, 27
	s_mov_b64 s[10:11], 0
	s_nop 3
	global_load_dword v0, v3, s[8:9] sc1
	s_waitcnt vmcnt(0)
	v_cmp_lt_u32_e32 vcc, v0, v6
	s_and_saveexec_b64 s[8:9], vcc
	s_cbranch_execz .LBB0_1320
	s_mov_b32 s21, s15
	s_mov_b32 s20, 1
	s_branch .LBB0_1313

.LBB0_1315:
	v_readlane_b32 s14, v253, 26
	v_readlane_b32 s15, v253, 27
	s_add_i32 s20, s20, 1
	s_mov_b64 s[16:17], -1
	s_nop 2
	global_load_dword v0, v3, s[14:15] sc1
	s_waitcnt vmcnt(0)
	v_cmp_ge_u32_e32 vcc, v0, v6
	s_orn2_b64 s[14:15], vcc, exec
	s_branch .LBB0_1312

.LBB0_1483:
	s_or_b64 exec, exec, s[6:7]
	v_cvt_f32_u32_e32 v5, v2
	s_waitcnt vmcnt(0)
	v_readfirstlane_b32 s6, v4
	v_sub_u32_e32 v4, 0, v2
	v_rcp_iflag_f32_e32 v5, v5
	v_add_u32_e32 v6, s6, v1
	v_mul_f32_e32 v5, 0x4f7ffffe, v5
	v_cvt_u32_f32_e32 v5, v5
	v_mul_lo_u32 v1, v4, v5
	v_mul_hi_u32 v1, v5, v1
	v_add_u32_e32 v1, v5, v1
	v_mul_hi_u32 v1, v6, v1
	v_mul_lo_u32 v4, v1, v2
	v_sub_u32_e32 v4, v6, v4
	v_add_u32_e32 v5, 1, v1
	v_cmp_ge_u32_e32 vcc, v4, v2
	s_nop 1
	v_cndmask_b32_e32 v1, v1, v5, vcc
	v_sub_u32_e32 v5, v4, v2
	v_cndmask_b32_e32 v4, v4, v5, vcc
	v_add_u32_e32 v5, 1, v1
	v_cmp_ge_u32_e32 vcc, v4, v2
	v_add_u32_e32 v4, 1, v6
	s_nop 0
	v_cndmask_b32_e32 v1, v1, v5, vcc
	v_mul_lo_u32 v5, v2, v1
	v_add_u32_e32 v2, v5, v2
	v_cmp_ne_u32_e32 vcc, v4, v2
	s_and_saveexec_b64 s[6:7], vcc
	s_xor_b64 s[6:7], exec, s[6:7]
	s_cbranch_execz .LBB0_1497
	v_readlane_b32 s8, v253, 26
	v_readlane_b32 s9, v253, 27
	s_waitcnt lgkmcnt(0)
	v_add_u32_e32 v1, 1, v1
	v_mul_lo_u32 v1, v1, v0
	buffer_inv sc1
	s_nop 2
	global_load_dword v0, v3, s[8:9] sc1
	s_waitcnt vmcnt(0)
	v_cmp_lt_u32_e32 vcc, v0, v1
	s_and_saveexec_b64 s[8:9], vcc
	s_cbranch_execz .LBB0_1496
	s_mov_b32 s20, 1
	s_mov_b64 s[10:11], 0
	s_branch .LBB0_1487

.LBB0_1500:
	s_or_b64 exec, exec, s[8:9]
	s_waitcnt vmcnt(0)
	v_readfirstlane_b32 s6, v2
	v_cvt_f32_u32_e32 v2, v0
	v_sub_u32_e32 v4, 0, v0
	v_add_u32_e32 v1, s6, v1
	v_readlane_b32 s6, v253, 24
	v_rcp_iflag_f32_e32 v2, v2
	v_readlane_b32 s7, v253, 25
	s_mov_b64 s[8:9], 0
	v_mul_f32_e32 v2, 0x4f7ffffe, v2
	v_cvt_u32_f32_e32 v2, v2
	v_mul_lo_u32 v4, v4, v2
	v_mul_hi_u32 v4, v2, v4
	v_add_u32_e32 v2, v2, v4
	v_mul_hi_u32 v2, v1, v2
	v_mul_lo_u32 v4, v2, v0
	v_sub_u32_e32 v4, v1, v4
	v_cmp_ge_u32_e32 vcc, v4, v0
	v_add_u32_e32 v5, 1, v2
	v_add_u32_e32 v1, 1, v1
	v_cndmask_b32_e32 v2, v2, v5, vcc
	v_sub_u32_e32 v5, v4, v0
	v_cndmask_b32_e32 v4, v4, v5, vcc
	v_cmp_ge_u32_e32 vcc, v4, v0
	v_add_u32_e32 v4, 1, v2
	s_nop 0
	v_cndmask_b32_e32 v2, v2, v4, vcc
	v_mul_lo_u32 v4, v0, v2
	v_add_u32_e32 v0, v4, v0
	v_mov_b32_e32 v6, v0
	v_cmp_ne_u32_e32 vcc, v1, v0
	v_mov_b64_e32 v[0:1], s[6:7]
	s_and_saveexec_b64 s[6:7], vcc
	s_cbranch_execz .LBB0_1512
	v_readlane_b32 s8, v253, 26
	v_readlane_b32 s9, v253, 27
	s_mov_b64 s[10:11], 0
	s_nop 3
	global_load_dword v0, v3, s[8:9] sc1
	s_waitcnt vmcnt(0)
	v_cmp_lt_u32_e32 vcc, v0, v6
	s_and_saveexec_b64 s[8:9], vcc
	s_cbranch_execz .LBB0_1511
	s_mov_b32 s20, 1
	s_branch .LBB0_1504

.LBB0_1789:
	s_or_b64 exec, exec, s[6:7]
	v_cvt_f32_u32_e32 v5, v2
	s_waitcnt vmcnt(0)
	v_readfirstlane_b32 s6, v4
	v_sub_u32_e32 v4, 0, v2
	v_rcp_iflag_f32_e32 v5, v5
	v_add_u32_e32 v6, s6, v1
	v_mul_f32_e32 v5, 0x4f7ffffe, v5
	v_cvt_u32_f32_e32 v5, v5
	v_mul_lo_u32 v1, v4, v5
	v_mul_hi_u32 v1, v5, v1
	v_add_u32_e32 v1, v5, v1
	v_mul_hi_u32 v1, v6, v1
	v_mul_lo_u32 v4, v1, v2
	v_sub_u32_e32 v4, v6, v4
	v_add_u32_e32 v5, 1, v1
	v_cmp_ge_u32_e32 vcc, v4, v2
	s_nop 1
	v_cndmask_b32_e32 v1, v1, v5, vcc
	v_sub_u32_e32 v5, v4, v2
	v_cndmask_b32_e32 v4, v4, v5, vcc
	v_add_u32_e32 v5, 1, v1
	v_cmp_ge_u32_e32 vcc, v4, v2
	v_add_u32_e32 v4, 1, v6
	s_nop 0
	v_cndmask_b32_e32 v1, v1, v5, vcc
	v_mul_lo_u32 v5, v2, v1
	v_add_u32_e32 v2, v5, v2
	v_cmp_ne_u32_e32 vcc, v4, v2
	s_and_saveexec_b64 s[6:7], vcc
	s_xor_b64 s[6:7], exec, s[6:7]
	s_cbranch_execz .LBB0_1803
	v_readlane_b32 s8, v253, 26
	v_readlane_b32 s9, v253, 27
	s_waitcnt lgkmcnt(0)
	v_add_u32_e32 v1, 1, v1
	v_mul_lo_u32 v1, v1, v0
	buffer_inv sc1
	s_nop 2
	global_load_dword v0, v3, s[8:9] sc1
	s_waitcnt vmcnt(0)
	v_cmp_lt_u32_e32 vcc, v0, v1
	s_and_saveexec_b64 s[8:9], vcc
	s_cbranch_execz .LBB0_1802
	s_mov_b32 s21, 1
	s_mov_b64 s[10:11], 0
	s_branch .LBB0_1793

.LBB0_1795:
	v_readlane_b32 s14, v253, 26
	v_readlane_b32 s15, v253, 27
	s_add_i32 s21, s21, 1
	s_mov_b64 s[16:17], -1
	s_nop 2
	global_load_dword v0, v3, s[14:15] sc1
	s_waitcnt vmcnt(0)
	v_cmp_ge_u32_e32 vcc, v0, v1
	s_orn2_b64 s[14:15], vcc, exec
	s_branch .LBB0_1792

.LBB0_1806:
	s_or_b64 exec, exec, s[8:9]
	s_waitcnt vmcnt(0)
	v_readfirstlane_b32 s6, v2
	v_cvt_f32_u32_e32 v2, v0
	v_sub_u32_e32 v4, 0, v0
	v_add_u32_e32 v1, s6, v1
	v_readlane_b32 s6, v253, 24
	v_rcp_iflag_f32_e32 v2, v2
	v_readlane_b32 s7, v253, 25
	s_mov_b64 s[8:9], 0
	v_mul_f32_e32 v2, 0x4f7ffffe, v2
	v_cvt_u32_f32_e32 v2, v2
	v_mul_lo_u32 v4, v4, v2
	v_mul_hi_u32 v4, v2, v4
	v_add_u32_e32 v2, v2, v4
	v_mul_hi_u32 v2, v1, v2
	v_mul_lo_u32 v4, v2, v0
	v_sub_u32_e32 v4, v1, v4
	v_cmp_ge_u32_e32 vcc, v4, v0
	v_add_u32_e32 v5, 1, v2
	v_add_u32_e32 v1, 1, v1
	v_cndmask_b32_e32 v2, v2, v5, vcc
	v_sub_u32_e32 v5, v4, v0
	v_cndmask_b32_e32 v4, v4, v5, vcc
	v_cmp_ge_u32_e32 vcc, v4, v0
	v_add_u32_e32 v4, 1, v2
	s_nop 0
	v_cndmask_b32_e32 v2, v2, v4, vcc
	v_mul_lo_u32 v4, v0, v2
	v_add_u32_e32 v0, v4, v0
	v_mov_b32_e32 v6, v0
	v_cmp_ne_u32_e32 vcc, v1, v0
	v_mov_b64_e32 v[0:1], s[6:7]
	s_and_saveexec_b64 s[6:7], vcc
	s_cbranch_execz .LBB0_1818
	v_readlane_b32 s8, v253, 26
	v_readlane_b32 s9, v253, 27
	s_mov_b64 s[10:11], 0
	s_nop 3
	global_load_dword v0, v3, s[8:9] sc1
	s_waitcnt vmcnt(0)
	v_cmp_lt_u32_e32 vcc, v0, v6
	s_and_saveexec_b64 s[8:9], vcc
	s_cbranch_execz .LBB0_1817
	s_mov_b32 s21, 1
	s_branch .LBB0_1810

.LBB0_1812:
	v_readlane_b32 s14, v253, 26
	v_readlane_b32 s15, v253, 27
	s_add_i32 s21, s21, 1
	s_mov_b64 s[16:17], -1
	s_nop 2
	global_load_dword v0, v3, s[14:15] sc1
	s_waitcnt vmcnt(0)
	v_cmp_ge_u32_e32 vcc, v0, v6
	s_orn2_b64 s[14:15], vcc, exec
	s_branch .LBB0_1809

.LBB0_1945:
	s_or_b64 exec, exec, s[6:7]
	v_cvt_f32_u32_e32 v5, v2
	s_waitcnt vmcnt(0)
	v_readfirstlane_b32 s6, v4
	v_sub_u32_e32 v4, 0, v2
	v_rcp_iflag_f32_e32 v5, v5
	v_add_u32_e32 v6, s6, v1
	v_mul_f32_e32 v5, 0x4f7ffffe, v5
	v_cvt_u32_f32_e32 v5, v5
	v_mul_lo_u32 v1, v4, v5
	v_mul_hi_u32 v1, v5, v1
	v_add_u32_e32 v1, v5, v1
	v_mul_hi_u32 v1, v6, v1
	v_mul_lo_u32 v4, v1, v2
	v_sub_u32_e32 v4, v6, v4
	v_add_u32_e32 v5, 1, v1
	v_cmp_ge_u32_e32 vcc, v4, v2
	s_nop 1
	v_cndmask_b32_e32 v1, v1, v5, vcc
	v_sub_u32_e32 v5, v4, v2
	v_cndmask_b32_e32 v4, v4, v5, vcc
	v_add_u32_e32 v5, 1, v1
	v_cmp_ge_u32_e32 vcc, v4, v2
	v_add_u32_e32 v4, 1, v6
	s_nop 0
	v_cndmask_b32_e32 v1, v1, v5, vcc
	v_mul_lo_u32 v5, v2, v1
	v_add_u32_e32 v2, v5, v2
	v_cmp_ne_u32_e32 vcc, v4, v2
	s_and_saveexec_b64 s[6:7], vcc
	s_xor_b64 s[6:7], exec, s[6:7]
	s_cbranch_execz .LBB0_1959
	v_readlane_b32 s10, v253, 26
	v_readlane_b32 s11, v253, 27
	s_waitcnt lgkmcnt(0)
	v_add_u32_e32 v1, 1, v1
	v_mul_lo_u32 v1, v1, v0
	buffer_inv sc1
	s_nop 2
	global_load_dword v0, v3, s[10:11] sc1
	s_waitcnt vmcnt(0)
	v_cmp_lt_u32_e32 vcc, v0, v1
	s_and_saveexec_b64 s[10:11], vcc
	s_cbranch_execz .LBB0_1958
	s_mov_b32 s22, 1
	s_mov_b64 s[12:13], 0
	s_branch .LBB0_1949

.LBB0_1951:
	v_readlane_b32 s16, v253, 26
	v_readlane_b32 s17, v253, 27
	s_add_i32 s22, s22, 1
	s_mov_b64 s[18:19], -1
	s_nop 2
	global_load_dword v0, v3, s[16:17] sc1
	s_waitcnt vmcnt(0)
	v_cmp_ge_u32_e32 vcc, v0, v1
	s_orn2_b64 s[16:17], vcc, exec
	s_branch .LBB0_1948

.LBB0_1962:
	s_or_b64 exec, exec, s[10:11]
	s_waitcnt vmcnt(0)
	v_readfirstlane_b32 s6, v2
	v_cvt_f32_u32_e32 v2, v0
	v_sub_u32_e32 v4, 0, v0
	v_add_u32_e32 v1, s6, v1
	v_readlane_b32 s6, v253, 24
	v_rcp_iflag_f32_e32 v2, v2
	v_readlane_b32 s7, v253, 25
	s_mov_b64 s[10:11], 0
	v_mul_f32_e32 v2, 0x4f7ffffe, v2
	v_cvt_u32_f32_e32 v2, v2
	v_mul_lo_u32 v4, v4, v2
	v_mul_hi_u32 v4, v2, v4
	v_add_u32_e32 v2, v2, v4
	v_mul_hi_u32 v2, v1, v2
	v_mul_lo_u32 v4, v2, v0
	v_sub_u32_e32 v4, v1, v4
	v_cmp_ge_u32_e32 vcc, v4, v0
	v_add_u32_e32 v5, 1, v2
	v_add_u32_e32 v1, 1, v1
	v_cndmask_b32_e32 v2, v2, v5, vcc
	v_sub_u32_e32 v5, v4, v0
	v_cndmask_b32_e32 v4, v4, v5, vcc
	v_cmp_ge_u32_e32 vcc, v4, v0
	v_add_u32_e32 v4, 1, v2
	s_nop 0
	v_cndmask_b32_e32 v2, v2, v4, vcc
	v_mul_lo_u32 v4, v0, v2
	v_add_u32_e32 v0, v4, v0
	v_mov_b32_e32 v6, v0
	v_cmp_ne_u32_e32 vcc, v1, v0
	v_mov_b64_e32 v[0:1], s[6:7]
	s_and_saveexec_b64 s[6:7], vcc
	s_cbranch_execz .LBB0_1974
	v_readlane_b32 s10, v253, 26
	v_readlane_b32 s11, v253, 27
	s_mov_b64 s[12:13], 0
	s_nop 3
	global_load_dword v0, v3, s[10:11] sc1
	s_waitcnt vmcnt(0)
	v_cmp_lt_u32_e32 vcc, v0, v6
	s_and_saveexec_b64 s[10:11], vcc
	s_cbranch_execz .LBB0_1973
	s_mov_b32 s22, 1
	s_branch .LBB0_1966

.LBB0_1968:
	v_readlane_b32 s16, v253, 26
	v_readlane_b32 s17, v253, 27
	s_add_i32 s22, s22, 1
	s_mov_b64 s[18:19], -1
	s_nop 2
	global_load_dword v0, v3, s[16:17] sc1
	s_waitcnt vmcnt(0)
	v_cmp_ge_u32_e32 vcc, v0, v6
	s_orn2_b64 s[16:17], vcc, exec
	s_branch .LBB0_1965

.LBB0_2054:
	s_or_b64 exec, exec, s[4:5]
	v_cvt_f32_u32_e32 v5, v2
	s_waitcnt vmcnt(0)
	v_readfirstlane_b32 s2, v4
	v_sub_u32_e32 v4, 0, v2
	v_rcp_iflag_f32_e32 v5, v5
	v_add_u32_e32 v6, s2, v1
	v_mul_f32_e32 v5, 0x4f7ffffe, v5
	v_cvt_u32_f32_e32 v5, v5
	v_mul_lo_u32 v1, v4, v5
	v_mul_hi_u32 v1, v5, v1
	v_add_u32_e32 v1, v5, v1
	v_mul_hi_u32 v1, v6, v1
	v_mul_lo_u32 v4, v1, v2
	v_sub_u32_e32 v4, v6, v4
	v_add_u32_e32 v5, 1, v1
	v_cmp_ge_u32_e32 vcc, v4, v2
	s_nop 1
	v_cndmask_b32_e32 v1, v1, v5, vcc
	v_sub_u32_e32 v5, v4, v2
	v_cndmask_b32_e32 v4, v4, v5, vcc
	v_add_u32_e32 v5, 1, v1
	v_cmp_ge_u32_e32 vcc, v4, v2
	v_add_u32_e32 v4, 1, v6
	s_nop 0
	v_cndmask_b32_e32 v1, v1, v5, vcc
	v_mul_lo_u32 v5, v2, v1
	v_add_u32_e32 v2, v5, v2
	v_cmp_ne_u32_e32 vcc, v4, v2
	s_and_saveexec_b64 s[4:5], vcc
	s_xor_b64 s[4:5], exec, s[4:5]
	s_cbranch_execz .LBB0_2068
	v_readlane_b32 s6, v253, 26
	v_readlane_b32 s7, v253, 27
	s_waitcnt lgkmcnt(0)
	v_add_u32_e32 v1, 1, v1
	v_mul_lo_u32 v1, v1, v0
	buffer_inv sc1
	s_nop 2
	global_load_dword v0, v3, s[6:7] sc1
	s_waitcnt vmcnt(0)
	v_cmp_lt_u32_e32 vcc, v0, v1
	s_and_saveexec_b64 s[6:7], vcc
	s_cbranch_execz .LBB0_2067
	s_mov_b32 s2, 1
	s_mov_b64 s[10:11], 0
	s_branch .LBB0_2058

.LBB0_2060:
	v_readlane_b32 s14, v253, 26
	v_readlane_b32 s15, v253, 27
	s_add_i32 s2, s2, 1
	s_mov_b64 s[16:17], -1
	s_nop 2
	global_load_dword v0, v3, s[14:15] sc1
	s_waitcnt vmcnt(0)
	v_cmp_ge_u32_e32 vcc, v0, v1
	s_orn2_b64 s[14:15], vcc, exec
	s_branch .LBB0_2057

.LBB0_2071:
	s_or_b64 exec, exec, s[6:7]
	s_waitcnt vmcnt(0)
	v_readfirstlane_b32 s2, v2
	v_cvt_f32_u32_e32 v2, v0
	v_sub_u32_e32 v4, 0, v0
	v_add_u32_e32 v1, s2, v1
	v_readlane_b32 s4, v253, 24
	v_rcp_iflag_f32_e32 v2, v2
	v_readlane_b32 s5, v253, 25
	s_mov_b64 s[6:7], 0
	v_mul_f32_e32 v2, 0x4f7ffffe, v2
	v_cvt_u32_f32_e32 v2, v2
	v_mul_lo_u32 v4, v4, v2
	v_mul_hi_u32 v4, v2, v4
	v_add_u32_e32 v2, v2, v4
	v_mul_hi_u32 v2, v1, v2
	v_mul_lo_u32 v4, v2, v0
	v_sub_u32_e32 v4, v1, v4
	v_cmp_ge_u32_e32 vcc, v4, v0
	v_add_u32_e32 v5, 1, v2
	v_add_u32_e32 v1, 1, v1
	v_cndmask_b32_e32 v2, v2, v5, vcc
	v_sub_u32_e32 v5, v4, v0
	v_cndmask_b32_e32 v4, v4, v5, vcc
	v_cmp_ge_u32_e32 vcc, v4, v0
	v_add_u32_e32 v4, 1, v2
	s_nop 0
	v_cndmask_b32_e32 v2, v2, v4, vcc
	v_mul_lo_u32 v4, v0, v2
	v_add_u32_e32 v0, v4, v0
	v_mov_b32_e32 v6, v0
	v_cmp_ne_u32_e32 vcc, v1, v0
	v_mov_b64_e32 v[0:1], s[4:5]
	s_and_saveexec_b64 s[4:5], vcc
	s_cbranch_execz .LBB0_2083
	v_readlane_b32 s6, v253, 26
	v_readlane_b32 s7, v253, 27
	s_mov_b64 s[10:11], 0
	s_nop 3
	global_load_dword v0, v3, s[6:7] sc1
	s_waitcnt vmcnt(0)
	v_cmp_lt_u32_e32 vcc, v0, v6
	s_and_saveexec_b64 s[6:7], vcc
	s_cbranch_execz .LBB0_2082
	s_mov_b32 s2, 1
	s_branch .LBB0_2075

.LBB0_2077:
	v_readlane_b32 s14, v253, 26
	v_readlane_b32 s15, v253, 27
	s_add_i32 s2, s2, 1
	s_mov_b64 s[16:17], -1
	s_nop 2
	global_load_dword v0, v3, s[14:15] sc1
	s_waitcnt vmcnt(0)
	v_cmp_ge_u32_e32 vcc, v0, v6
	s_orn2_b64 s[14:15], vcc, exec
	s_branch .LBB0_2074
